# v55 plus attention loop K/V load addresses as three running pointers (10 address VALU ops per tile become 3)
# baseline (speedup 1.0000x reference)
.LBB0_1764:
	s_bitcmp0_b32 s52, 0
	s_cselect_b32 s39, s8, s40
	s_add_i32 s39, s39, s4
	s_cmpk_gt_i32 s39, 0x7ff
	s_cbranch_scc1 .LBB0_1763
	s_lshl_b32 s4, s39, 10
	s_and_b32 s4, s4, 0x6000
	s_ashr_i32 s53, s39, 5
	v_mov_b64_e32 v[16:17], s[6:7]
	s_lshl_b32 s36, s39, 7
	v_add_u32_e32 v0, s4, v166
	s_sub_i32 s38, 63, s53
	s_and_b32 s57, s36, 0x380
	v_mad_i64_i32 v[0:1], s[36:37], v0, s44, v[16:17]
	v_add_u32_e32 v2, s4, v168
	s_lshl_b32 s56, s38, 7
	s_lshl_b32 s36, s57, 1
	s_mov_b32 s37, s5
	v_mad_i64_i32 v[2:3], s[54:55], v2, s44, v[16:17]
	v_lshl_add_u64 v[0:1], v[0:1], 0, s[36:37]
	v_lshl_add_u64 v[2:3], v[2:3], 0, s[36:37]
	v_mov_b32_e32 v177, v163
	s_add_i32 s37, s56, s41
	v_lshl_add_u64 v[42:43], v[2:3], 0, v[176:177]
	s_add_i32 s37, s37, s4
	v_add_co_u32_e32 v12, vcc, s46, v42
	v_or_b32_e32 v178, s37, v160
	s_or_b32 s4, s57, s42
	v_lshl_add_u64 v[40:41], v[0:1], 0, v[162:163]
	v_addc_co_u32_e32 v13, vcc, 0, v43, vcc
	v_mad_u64_u32 v[16:17], s[54:55], v178, s44, v[16:17]
	s_lshl_b32 s4, s4, 1
	global_load_dwordx4 v[0:3], v[40:41], off
	global_load_dwordx4 v[4:7], v[40:41], off offset:128
	global_load_dwordx4 v[8:11], v[42:43], off offset:2048
	s_nop 0
	global_load_dwordx4 v[12:15], v[12:13], off offset:2048
	v_lshl_add_u64 v[16:17], v[16:17], 0, s[4:5]
	v_lshl_add_u64 v[16:17], v[164:165], 1, v[16:17]
	v_add_co_u32_e32 v18, vcc, s45, v16
	v_add_u32_e32 v177, s43, v186
	s_nop 0
	v_addc_co_u32_e32 v19, vcc, 0, v17, vcc
	global_load_dwordx4 v[144:147], v[18:19], off
	v_lshl_add_u64 v[16:17], v[16:17], 0, s[30:31]
	global_load_dwordx4 v[148:151], v[16:17], off offset:32
	global_load_dwordx4 v[152:155], v[16:17], off offset:64
	global_load_dwordx4 v[140:143], v[16:17], off offset:96
	v_add_u32_e32 v54, 0, v182
	v_add_u32_e32 v200, s43, v187
	v_add_u32_e32 v201, s43, v188
	v_add_u32_e32 v180, s43, v189
	v_add_co_u32_e32 v40, vcc, s47, v40
	v_mov_b32_e32 v53, v163
	s_nop 0
	v_addc_co_u32_e32 v41, vcc, 0, v41, vcc
	v_add_co_u32_e32 v48, vcc, s47, v42
	s_mov_b32 s4, 0
	s_nop 0
	v_addc_co_u32_e32 v49, vcc, 0, v43, vcc
	v_add_co_u32_e32 v50, vcc, s48, v42
	s_cmp_eq_u32 s53, 63
	s_nop 0
	v_addc_co_u32_e32 v51, vcc, 0, v43, vcc
	s_nop 0
	global_load_dwordx4 v[236:239], v[40:41], off
	global_load_dwordx4 v[240:243], v[40:41], off offset:128
	global_load_dwordx4 v[244:247], v[48:49], off offset:2048
	global_load_dwordx4 v[248:251], v[50:51], off offset:2048
	s_waitcnt vmcnt(11)
	ds_write_b128 v183, v[0:3]
	s_waitcnt vmcnt(10)
	ds_write_b128 v183, v[4:7] offset:8192
	s_waitcnt vmcnt(9)
	ds_write_b128 v54, v[8:11] offset:32768
	s_waitcnt vmcnt(8)
	ds_write_b128 v54, v[12:15] offset:40960
	s_waitcnt vmcnt(4) lgkmcnt(0)
	s_barrier
	ds_read_b128 v[0:3], v177
	ds_read_b128 v[4:7], v177 offset:4096
	s_waitcnt lgkmcnt(1)
	v_mfma_f32_32x32x16_bf16 v[16:31], v[0:3], v[144:147], 0
	ds_read_b128 v[32:35], v200
	ds_read_b128 v[36:39], v200 offset:4096
	s_waitcnt lgkmcnt(1)
	v_mfma_f32_32x32x16_bf16 v[16:31], v[32:35], v[148:151], v[16:31]
	ds_read_b128 v[32:35], v201
	v_mfma_f32_32x32x16_bf16 v[0:15], v[4:7], v[144:147], 0
	s_waitcnt lgkmcnt(1)
	v_mfma_f32_32x32x16_bf16 v[0:15], v[36:39], v[148:151], v[0:15]
	ds_read_b128 v[36:39], v201 offset:4096
	s_waitcnt lgkmcnt(1)
	v_mfma_f32_32x32x16_bf16 v[16:31], v[32:35], v[152:155], v[16:31]
	ds_read_b128 v[32:35], v180
	s_waitcnt lgkmcnt(1)
	v_mfma_f32_32x32x16_bf16 v[0:15], v[36:39], v[152:155], v[0:15]
	ds_read_b128 v[44:47], v180 offset:4096
	s_waitcnt lgkmcnt(1)
	v_mfma_f32_32x32x16_bf16 v[16:31], v[32:35], v[140:143], v[16:31]
	s_waitcnt vmcnt(3)
	ds_write_b128 v183, v[236:239] offset:16384
	s_waitcnt vmcnt(2)
	ds_write_b128 v183, v[240:243] offset:24576
	s_waitcnt vmcnt(1)
	ds_write_b128 v54, v[244:247] offset:49152
	s_waitcnt vmcnt(0)
	ds_write_b128 v54, v[248:251] offset:57344
	s_waitcnt lgkmcnt(4)
	v_mfma_f32_32x32x16_bf16 v[0:15], v[44:47], v[140:143], v[0:15]
	v_exp_f32_e32 v44, v16
	v_exp_f32_e32 v45, v17
	v_exp_f32_e32 v16, v18
	v_exp_f32_e32 v52, v19
	v_exp_f32_e32 v46, v20
	v_add_f32_e32 v17, v44, v45
	v_exp_f32_e32 v21, v21
	v_cvt_pk_bf16_f32 v157, v16, v52
	v_pk_add_f32 v[16:17], v[16:17], v[52:53]
	v_exp_f32_e32 v18, v22
	v_pk_add_f32 v[16:17], v[16:17], v[16:17] op_sel_hi:[0,1]
	v_exp_f32_e32 v24, v24
	v_exp_f32_e32 v25, v25
	v_exp_f32_e32 v16, v23
	v_add_f32_e32 v19, v46, v21
	v_cvt_pk_bf16_f32 v158, v46, v21
	v_add_f32_e32 v21, v24, v25
	v_cvt_pk_bf16_f32 v136, v24, v25
	v_pk_add_f32 v[24:25], v[18:19], v[16:17]
	v_exp_f32_e32 v20, v26
	v_pk_add_f32 v[24:25], v[24:25], v[24:25] op_sel_hi:[0,1]
	v_exp_f32_e32 v26, v28
	v_exp_f32_e32 v28, v29
	v_exp_f32_e32 v24, v27
	v_exp_f32_e32 v22, v30
	v_exp_f32_e32 v29, v0
	v_add_f32_e32 v23, v26, v28
	v_cvt_pk_bf16_f32 v138, v26, v28
	v_pk_add_f32 v[26:27], v[20:21], v[24:25]
	v_exp_f32_e32 v30, v1
	v_pk_add_f32 v[26:27], v[26:27], v[26:27] op_sel_hi:[0,1]
	v_exp_f32_e32 v26, v31
	v_exp_f32_e32 v0, v3
	v_add_f32_e32 v1, v29, v30
	v_cvt_pk_bf16_f32 v132, v29, v30
	v_pk_add_f32 v[28:29], v[22:23], v[26:27]
	v_exp_f32_e32 v3, v4
	v_pk_add_f32 v[28:29], v[28:29], v[28:29] op_sel_hi:[0,1]
	v_exp_f32_e32 v47, v5
	v_exp_f32_e32 v28, v2
	v_exp_f32_e32 v4, v6
	v_exp_f32_e32 v6, v8
	v_add_f32_e32 v5, v3, v47
	v_cvt_pk_bf16_f32 v134, v3, v47
	v_pk_add_f32 v[2:3], v[28:29], v[0:1]
	v_cvt_pk_bf16_f32 v133, v28, v0
	v_pk_add_f32 v[2:3], v[2:3], v[2:3] op_sel_hi:[0,1]
	v_exp_f32_e32 v2, v7
	v_exp_f32_e32 v55, v9
	v_exp_f32_e32 v8, v10
	v_exp_f32_e32 v10, v12
	v_pk_add_f32 v[0:1], v[4:5], v[2:3]
	v_add_f32_e32 v9, v6, v55
	v_pk_add_f32 v[0:1], v[0:1], v[0:1] op_sel_hi:[0,1]
	v_exp_f32_e32 v0, v11
	v_cvt_pk_bf16_f32 v135, v4, v2
	v_exp_f32_e32 v56, v13
	v_exp_f32_e32 v12, v14
	v_pk_add_f32 v[2:3], v[8:9], v[0:1]
	v_cvt_pk_bf16_f32 v129, v8, v0
	v_pk_add_f32 v[2:3], v[2:3], v[2:3] op_sel_hi:[0,1]
	v_exp_f32_e32 v2, v15
	v_add_f32_e32 v13, v10, v56
	v_cvt_pk_bf16_f32 v156, v44, v45
	v_cvt_pk_bf16_f32 v128, v6, v55
	v_pk_add_f32 v[0:1], v[12:13], v[2:3]
	v_cvt_pk_bf16_f32 v130, v10, v56
	v_cvt_pk_bf16_f32 v159, v18, v16
	v_cvt_pk_bf16_f32 v137, v20, v24
	v_cvt_pk_bf16_f32 v139, v22, v26
	v_cvt_pk_bf16_f32 v131, v12, v2
	v_add_f32_e32 v181, v0, v1
	s_waitcnt lgkmcnt(0)
	s_barrier
	s_cbranch_scc1 .LBB0_1769
	s_bfe_u32 s37, s39, 0x20003
	s_and_b32 s4, s39, 7
	v_mad_u64_u32 v[96:97], s[54:55], s37, v199, v[172:173]
	v_mad_u64_u32 v[98:99], s[54:55], s37, v199, v[174:175]
	v_mov_b32_e32 v0, 0
	s_mov_b32 s53, 1
	s_lshl_b32 s38, s38, 1
	s_lshl_b32 s4, s4, 8
	s_mov_b32 s54, 0
	s_movk_i32 s39, 0x4000
	v_mov_b32_e32 v1, v0
	v_mov_b32_e32 v2, v0
	v_mov_b32_e32 v3, v0
	v_mov_b32_e32 v4, v0
	v_mov_b32_e32 v5, v0
	v_mov_b32_e32 v6, v0
	v_mov_b32_e32 v7, v0
	v_mov_b32_e32 v8, v0
	v_mov_b32_e32 v9, v0
	v_mov_b32_e32 v10, v0
	v_mov_b32_e32 v11, v0
	v_mov_b32_e32 v12, v0
	v_mov_b32_e32 v13, v0
	v_mov_b32_e32 v14, v0
	v_mov_b32_e32 v15, v0
	v_mov_b32_e32 v48, v0
	v_mov_b32_e32 v49, v0
	v_mov_b32_e32 v50, v0
	v_mov_b32_e32 v51, v0
	v_mov_b32_e32 v52, v0
	v_mov_b32_e32 v53, v0
	v_mov_b32_e32 v54, v0
	v_mov_b32_e32 v55, v0
	v_mov_b32_e32 v56, v0
	v_mov_b32_e32 v57, v0
	v_mov_b32_e32 v58, v0
	v_mov_b32_e32 v59, v0
	v_mov_b32_e32 v60, v0
	v_mov_b32_e32 v61, v0
	v_mov_b32_e32 v62, v0
	v_mov_b32_e32 v63, v0
	v_mov_b32_e32 v32, v0
	v_mov_b32_e32 v33, v0
	v_mov_b32_e32 v34, v0
	v_mov_b32_e32 v35, v0
	v_mov_b32_e32 v36, v0
	v_mov_b32_e32 v37, v0
	v_mov_b32_e32 v38, v0
	v_mov_b32_e32 v39, v0
	v_mov_b32_e32 v40, v0
	v_mov_b32_e32 v41, v0
	v_mov_b32_e32 v42, v0
	v_mov_b32_e32 v43, v0
	v_mov_b32_e32 v44, v0
	v_mov_b32_e32 v45, v0
	v_mov_b32_e32 v46, v0
	v_mov_b32_e32 v47, v0
	v_mov_b32_e32 v16, v0
	v_mov_b32_e32 v17, v0
	v_mov_b32_e32 v18, v0
	v_mov_b32_e32 v19, v0
	v_mov_b32_e32 v20, v0
	v_mov_b32_e32 v21, v0
	v_mov_b32_e32 v22, v0
	v_mov_b32_e32 v23, v0
	v_mov_b32_e32 v24, v0
	v_mov_b32_e32 v25, v0
	v_mov_b32_e32 v26, v0
	v_mov_b32_e32 v27, v0
	v_mov_b32_e32 v28, v0
	v_mov_b32_e32 v29, v0
	v_mov_b32_e32 v30, v0
	v_mov_b32_e32 v31, v0
	v_lshl_add_u64 v[98:99], v[98:99], 0, s[4:5]
	v_lshl_add_u64 v[96:97], v[96:97], 0, s[4:5]
	v_add_co_u32_e32 v98, vcc, s49, v98
	s_nop 1
	v_addc_co_u32_e32 v99, vcc, 0, v99, vcc
	v_add_co_u32_e32 v96, vcc, s49, v96
	s_nop 1
	v_addc_co_u32_e32 v97, vcc, 0, v97, vcc
	v_add_co_u32_e32 v226, vcc, 0x30000, v96
	s_nop 1
	v_addc_co_u32_e32 v227, vcc, 0, v97, vcc
.LBB0_1767:
	s_and_b32 s37, s39, 0x4000
	s_lshl_b32 s54, s54, 14
	s_add_i32 s37, s43, s37
	s_add_i32 s54, s54, 0
	v_add_u32_e32 v68, s37, v186
	v_add_u32_e32 v106, s54, v190
	v_add_u32_e32 v114, s54, v194
	ds_read_b128 v[64:67], v68
	ds_read_b128 v[80:83], v68 offset:4096
	v_add_u32_e32 v122, s54, v191
	v_add_u32_e32 v126, s54, v195
	ds_read_b64_tr_b16 v[102:103], v114 offset:32768
	ds_read_b64_tr_b16 v[100:101], v106 offset:32768
	ds_read_b64_tr_b16 v[104:105], v106 offset:36864
	ds_read_b64_tr_b16 v[108:109], v106 offset:40960
	ds_read_b64_tr_b16 v[112:113], v106 offset:45056
	ds_read_b64_tr_b16 v[106:107], v114 offset:36864
	ds_read_b64_tr_b16 v[110:111], v114 offset:40960
	ds_read_b64_tr_b16 v[114:115], v114 offset:45056
	ds_read_b64_tr_b16 v[118:119], v126 offset:32768
	ds_read_b64_tr_b16 v[116:117], v122 offset:32768
	ds_read_b64_tr_b16 v[120:121], v122 offset:36864
	v_add_u32_e32 v208, s54, v192
	v_add_u32_e32 v212, s54, v196
	s_waitcnt lgkmcnt(9)
	v_mfma_f32_32x32x16_bf16 v[0:15], v[100:103], v[156:159], v[0:15]
	ds_read_b64_tr_b16 v[100:101], v122 offset:40960
	ds_read_b64_tr_b16 v[124:125], v122 offset:45056
	ds_read_b64_tr_b16 v[122:123], v126 offset:36864
	ds_read_b64_tr_b16 v[102:103], v126 offset:40960
	ds_read_b64_tr_b16 v[126:127], v126 offset:45056
	ds_read_b64_tr_b16 v[202:203], v208 offset:32768
	ds_read_b64_tr_b16 v[204:205], v212 offset:32768
	v_add_u32_e32 v224, s54, v197
	v_add_u32_e32 v220, s54, v193
	v_add_u32_e32 v179, s37, v187
	s_mov_b32 s54, s53
	s_waitcnt lgkmcnt(8)
	v_mfma_f32_32x32x16_bf16 v[48:63], v[116:119], v[156:159], v[48:63]
	ds_read_b64_tr_b16 v[116:117], v208 offset:36864
	ds_read_b64_tr_b16 v[206:207], v208 offset:40960
	ds_read_b64_tr_b16 v[210:211], v208 offset:45056
	ds_read_b64_tr_b16 v[118:119], v212 offset:36864
	ds_read_b64_tr_b16 v[208:209], v212 offset:40960
	ds_read_b64_tr_b16 v[212:213], v212 offset:45056
	ds_read_b64_tr_b16 v[216:217], v224 offset:32768
	v_mfma_f32_32x32x16_bf16 v[64:79], v[64:67], v[144:147], 0
	v_mfma_f32_32x32x16_bf16 v[80:95], v[80:83], v[144:147], 0
	s_waitcnt lgkmcnt(7)
	v_mfma_f32_32x32x16_bf16 v[32:47], v[202:205], v[156:159], v[32:47]
	ds_read_b64_tr_b16 v[214:215], v220 offset:32768
	ds_read_b64_tr_b16 v[202:203], v220 offset:36864
	ds_read_b64_tr_b16 v[218:219], v220 offset:40960
	ds_read_b64_tr_b16 v[222:223], v220 offset:45056
	ds_read_b64_tr_b16 v[204:205], v224 offset:36864
	ds_read_b64_tr_b16 v[220:221], v224 offset:40960
	ds_read_b64_tr_b16 v[224:225], v224 offset:45056
	s_waitcnt lgkmcnt(6)
	v_mfma_f32_32x32x16_bf16 v[16:31], v[214:217], v[156:159], v[16:31]
	ds_read_b128 v[156:159], v179
	ds_read_b128 v[214:217], v179 offset:4096
	s_waitcnt lgkmcnt(1)
	v_mfma_f32_32x32x16_bf16 v[64:79], v[156:159], v[148:151], v[64:79]
	s_waitcnt lgkmcnt(0)
	v_mfma_f32_32x32x16_bf16 v[80:95], v[214:217], v[148:151], v[80:95]
	v_mfma_f32_32x32x16_bf16 v[32:47], v[116:119], v[136:139], v[32:47]
	v_add_u32_e32 v116, s37, v188
	v_mfma_f32_32x32x16_bf16 v[0:15], v[104:107], v[136:139], v[0:15]
	ds_read_b128 v[104:107], v116
	ds_read_b128 v[116:119], v116 offset:4096
	v_mfma_f32_32x32x16_bf16 v[48:63], v[120:123], v[136:139], v[48:63]
	s_waitcnt lgkmcnt(1)
	v_mfma_f32_32x32x16_bf16 v[64:79], v[104:107], v[152:155], v[64:79]
	v_add_u32_e32 v104, s37, v189
	s_add_i32 s37, s53, 1
	s_cmp_lg_u32 s53, 2
	s_cselect_b32 s53, s37, 0
	s_addk_i32 s39, 0x4000
	s_lshl_b32 s37, s53, 14
	s_add_i32 s38, s38, -1
	s_waitcnt lgkmcnt(0)
	v_mfma_f32_32x32x16_bf16 v[80:95], v[116:119], v[152:155], v[80:95]
	s_and_b32 s55, s39, 0x4000
	s_add_i32 s56, s37, 0
	v_add_u32_e32 v116, s55, v183
	s_cmp_eq_u32 s38, 0
	v_add_u32_e32 v117, s56, v182
	v_mfma_f32_32x32x16_bf16 v[48:63], v[100:103], v[132:135], v[48:63]
	ds_read_b128 v[100:103], v104
	ds_read_b128 v[104:107], v104 offset:4096
	v_mfma_f32_32x32x16_bf16 v[0:15], v[108:111], v[132:135], v[0:15]
	s_waitcnt lgkmcnt(1)
	v_mfma_f32_32x32x16_bf16 v[64:79], v[100:103], v[140:143], v[64:79]
	s_waitcnt lgkmcnt(0)
	v_mfma_f32_32x32x16_bf16 v[80:95], v[104:107], v[140:143], v[80:95]
	global_load_dwordx4 v[100:103], v[98:99], off
	global_load_dwordx4 v[104:107], v[98:99], off offset:128
	s_nop 7
	v_exp_f32_e32 v118, v64
	v_mfma_f32_32x32x16_bf16 v[0:15], v[112:115], v[128:131], v[0:15]
	v_exp_f32_e32 v65, v65
	global_load_dwordx4 v[108:111], v[96:97], off offset:2048
	global_load_dwordx4 v[112:115], v[226:227], off offset:2048
	v_lshl_add_u64 v[98:99], v[98:99], 0, s[34:35]
	v_lshl_add_u64 v[96:97], v[96:97], 0, s[34:35]
	v_lshl_add_u64 v[226:227], v[226:227], 0, s[34:35]
	v_exp_f32_e32 v119, v66
	v_exp_f32_e32 v67, v67
	v_exp_f32_e32 v64, v68
	v_exp_f32_e32 v66, v69
	v_exp_f32_e32 v122, v81
	v_exp_f32_e32 v81, v82
	v_exp_f32_e32 v82, v92
	v_add_f32_e32 v92, v118, v65
	v_cvt_pk_bf16_f32 v156, v118, v65
	v_add_f32_e32 v65, v119, v67
	v_cvt_pk_bf16_f32 v157, v119, v67
	v_add_f32_e32 v67, v181, v92
	v_cvt_pk_bf16_f32 v158, v64, v66
	v_add_f32_e32 v64, v64, v66
	v_add_f32_e32 v65, v65, v67
	v_exp_f32_e32 v120, v70
	v_exp_f32_e32 v71, v71
	v_add_f32_e32 v65, v64, v65
	v_exp_f32_e32 v68, v72
	v_exp_f32_e32 v64, v73
	v_mfma_f32_32x32x16_bf16 v[16:31], v[202:205], v[136:139], v[16:31]
	v_exp_f32_e32 v74, v74
	v_exp_f32_e32 v121, v75
	v_exp_f32_e32 v70, v76
	v_exp_f32_e32 v72, v77
	v_add_f32_e32 v69, v120, v71
	v_add_f32_e32 v66, v68, v64
	v_add_f32_e32 v67, v69, v65
	v_exp_f32_e32 v77, v78
	v_exp_f32_e32 v79, v79
	v_cvt_pk_bf16_f32 v136, v68, v64
	v_add_f32_e32 v65, v66, v67
	v_exp_f32_e32 v75, v80
	v_cvt_pk_bf16_f32 v159, v120, v71
	v_add_f32_e32 v71, v74, v121
	v_mov_b32_e32 v73, v65
	v_add_f32_e32 v64, v70, v72
	v_add_f32_e32 v65, v71, v73
	v_exp_f32_e32 v83, v83
	v_add_f32_e32 v64, v64, v65
	v_mfma_f32_32x32x16_bf16 v[32:47], v[206:209], v[132:135], v[32:47]
	v_exp_f32_e32 v76, v84
	v_exp_f32_e32 v78, v85
	v_cvt_pk_bf16_f32 v137, v74, v121
	v_add_f32_e32 v74, v77, v79
	v_mov_b32_e32 v65, v122
	v_add_f32_e32 v64, v74, v64
	v_add_f32_e32 v65, v75, v65
	v_cvt_pk_bf16_f32 v139, v77, v79
	v_mfma_f32_32x32x16_bf16 v[16:31], v[218:221], v[132:135], v[16:31]
	v_add_f32_e32 v65, v64, v65
	v_add_f32_e32 v77, v81, v83
	v_mov_b32_e32 v79, v65
	v_add_f32_e32 v64, v76, v78
	v_add_f32_e32 v65, v77, v79
	v_exp_f32_e32 v85, v86
	v_exp_f32_e32 v86, v87
	v_add_f32_e32 v65, v64, v65
	v_exp_f32_e32 v80, v88
	v_exp_f32_e32 v64, v89
	v_mfma_f32_32x32x16_bf16 v[48:63], v[124:127], v[128:131], v[48:63]
	v_exp_f32_e32 v87, v90
	v_exp_f32_e32 v88, v91
	v_exp_f32_e32 v84, v93
	v_cvt_pk_bf16_f32 v133, v81, v83
	v_add_f32_e32 v81, v85, v86
	v_exp_f32_e32 v90, v94
	v_exp_f32_e32 v91, v95
	v_mfma_f32_32x32x16_bf16 v[32:47], v[210:213], v[128:131], v[32:47]
	v_add_f32_e64 v66, v80, v64
	v_add_f32_e64 v67, v81, v65
	v_cvt_pk_bf16_f32 v135, v85, v86
	v_add_f32_e32 v83, v87, v88
	v_add_f32_e32 v86, v90, v91
	v_cvt_pk_bf16_f32 v138, v70, v72
	v_cvt_pk_bf16_f32 v132, v75, v122
	v_cvt_pk_bf16_f32 v134, v76, v78
	v_mfma_f32_32x32x16_bf16 v[16:31], v[222:225], v[128:131], v[16:31]
	v_cvt_pk_bf16_f32 v128, v80, v64
	v_add_f32_e64 v64, v66, v66
	v_add_f32_e64 v65, v66, v67
	v_mov_b32_e32 v85, v65
	v_add_f32_e64 v64, v82, v84
	v_add_f32_e64 v65, v83, v85
	v_cvt_pk_bf16_f32 v129, v87, v88
	v_add_f32_e32 v64, v64, v65
	v_cvt_pk_bf16_f32 v130, v82, v84
	v_cvt_pk_bf16_f32 v131, v90, v91
	v_add_f32_e32 v181, v86, v64
	s_waitcnt vmcnt(3)
	ds_write_b128 v116, v[100:103]
	s_waitcnt vmcnt(2)
	ds_write_b128 v116, v[104:107] offset:8192
	s_waitcnt vmcnt(1)
	ds_write_b128 v117, v[108:111] offset:32768
	s_waitcnt vmcnt(0)
	ds_write_b128 v117, v[112:115] offset:40960
	s_waitcnt lgkmcnt(0)
	s_barrier
	s_cbranch_scc0 .LBB0_1767
	s_lshl_b32 s4, s54, 14
	s_branch .LBB0_1770
